# code placement: the six GEMM K-loop heads aligned to 64 bytes (.p2align 6)
# baseline (speedup 1.0000x reference)
; template <class Epi, class Sched, bool ALIGN_EPI = false, bool SP2 = false>
; __device__ __forceinline__ void gemm_phase(PG8_LAS unsigned char* lds, const Gemm g, const Sched& S, const Epi& E) {
;     ...
;         for (int t = 0; t < nt; t += 2) {
;             const bool last = (t == nt - 2);
.Lprio_done_86:
	.p2align	6
